# attention work queue: ticket atomic issued at the start of the last key-tile step
# baseline (speedup 1.0000x reference)
.Lf3_tail5:
	s_cmp_lg_u32 s33, 0
	s_cbranch_scc1 .Lq_pff
	s_mov_b64 s[12:13], exec
	s_mov_b64 exec, 1
	v_mov_b32_e32 v176, 1
	global_atomic_add v176, v13, v176, s[8:9] sc0
	s_mov_b64 exec, s[12:13]
